# nt cache hint on the in-proj gate-tile stores only (gates are not re-read until the branch phase)
# baseline (speedup 1.0000x reference)
.LBB0_244:
	s_lshl_b32 s9, s35, 3
	s_lshl_b32 s7, s36, 7
	s_add_i32 s9, s30, s9
	s_add_i32 s14, s9, s7
	s_ashr_i32 s15, s14, 31
	s_lshl_b64 s[14:15], s[14:15], 14
	v_lshl_add_u64 v[156:157], v[138:139], 0, s[14:15]
	v_mul_f32_e32 v96, 0xbfb8aa3b, v96
	v_mul_f32_e32 v97, 0xbfb8aa3b, v97
	v_exp_f32_e32 v96, v96
	v_exp_f32_e32 v97, v97
	v_add_f32_e32 v96, 1.0, v96
	v_add_f32_e32 v97, 1.0, v97
	v_rcp_f32_e32 v96, v96
	v_rcp_f32_e32 v97, v97
	s_nop 0
	v_cvt_pk_bf16_f32 v97, v96, v97
	v_mul_f32_e32 v94, 0xbfb8aa3b, v94
	v_mul_f32_e32 v95, 0xbfb8aa3b, v95
	v_exp_f32_e32 v94, v94
	v_exp_f32_e32 v95, v95
	v_add_f32_e32 v94, 1.0, v94
	v_add_f32_e32 v95, 1.0, v95
	v_rcp_f32_e32 v94, v94
	v_rcp_f32_e32 v95, v95
	s_nop 0
	v_cvt_pk_bf16_f32 v96, v94, v95
	v_mul_f32_e32 v90, 0xbfb8aa3b, v90
	v_mul_f32_e32 v91, 0xbfb8aa3b, v91
	v_exp_f32_e32 v90, v90
	v_exp_f32_e32 v91, v91
	v_add_f32_e32 v90, 1.0, v90
	v_add_f32_e32 v91, 1.0, v91
	v_rcp_f32_e32 v90, v90
	v_rcp_f32_e32 v91, v91
	s_nop 0
	v_cvt_pk_bf16_f32 v94, v90, v91
	v_add_co_u32_e32 v90, vcc, s63, v156
	s_movk_i32 s7, 0x2000
	s_nop 0
	v_addc_co_u32_e32 v91, vcc, 0, v157, vcc
	v_mul_f32_e32 v92, 0xbfb8aa3b, v92
	v_mul_f32_e32 v93, 0xbfb8aa3b, v93
	v_exp_f32_e32 v92, v92
	v_exp_f32_e32 v93, v93
	v_add_f32_e32 v92, 1.0, v92
	v_add_f32_e32 v93, 1.0, v93
	v_rcp_f32_e32 v92, v92
	v_rcp_f32_e32 v93, v93
	s_nop 0
	v_cvt_pk_bf16_f32 v95, v92, v93
	v_add_co_u32_e32 v92, vcc, s7, v156
	s_movk_i32 s7, 0x3000
	s_nop 0
	v_addc_co_u32_e32 v93, vcc, 0, v157, vcc
	v_mul_f32_e32 v32, 0xbfb8aa3b, v32
	v_mul_f32_e32 v33, 0xbfb8aa3b, v33
	v_exp_f32_e32 v32, v32
	v_exp_f32_e32 v33, v33
	v_add_f32_e32 v32, 1.0, v32
	v_add_f32_e32 v33, 1.0, v33
	v_rcp_f32_e32 v32, v32
	v_rcp_f32_e32 v33, v33
	s_nop 0
	v_cvt_pk_bf16_f32 v33, v32, v33
	v_mul_f32_e32 v30, 0xbfb8aa3b, v30
	v_mul_f32_e32 v31, 0xbfb8aa3b, v31
	v_exp_f32_e32 v30, v30
	v_exp_f32_e32 v31, v31
	v_add_f32_e32 v30, 1.0, v30
	v_add_f32_e32 v31, 1.0, v31
	v_rcp_f32_e32 v30, v30
	v_rcp_f32_e32 v31, v31
	s_nop 0
	v_cvt_pk_bf16_f32 v32, v30, v31
	v_mul_f32_e32 v26, 0xbfb8aa3b, v26
	v_mul_f32_e32 v27, 0xbfb8aa3b, v27
	v_exp_f32_e32 v26, v26
	v_exp_f32_e32 v27, v27
	v_add_f32_e32 v26, 1.0, v26
	v_add_f32_e32 v27, 1.0, v27
	v_rcp_f32_e32 v26, v26
	v_rcp_f32_e32 v27, v27
	s_nop 0
	v_cvt_pk_bf16_f32 v30, v26, v27
	v_add_co_u32_e32 v26, vcc, s7, v156
	v_mul_f32_e32 v128, 0xbfb8aa3b, v128
	v_mul_f32_e32 v129, 0xbfb8aa3b, v129
	v_exp_f32_e32 v128, v128
	v_exp_f32_e32 v129, v129
	v_add_f32_e32 v128, 1.0, v128
	v_add_f32_e32 v129, 1.0, v129
	v_rcp_f32_e32 v128, v128
	v_rcp_f32_e32 v129, v129
	s_nop 0
	v_cvt_pk_bf16_f32 v129, v128, v129
	v_mul_f32_e32 v126, 0xbfb8aa3b, v126
	v_mul_f32_e32 v127, 0xbfb8aa3b, v127
	v_exp_f32_e32 v126, v126
	v_exp_f32_e32 v127, v127
	v_add_f32_e32 v126, 1.0, v126
	v_add_f32_e32 v127, 1.0, v127
	v_rcp_f32_e32 v126, v126
	v_rcp_f32_e32 v127, v127
	s_nop 0
	v_cvt_pk_bf16_f32 v128, v126, v127
	v_mul_f32_e32 v124, 0xbfb8aa3b, v124
	v_mul_f32_e32 v125, 0xbfb8aa3b, v125
	v_exp_f32_e32 v124, v124
	v_exp_f32_e32 v125, v125
	v_add_f32_e32 v124, 1.0, v124
	v_add_f32_e32 v125, 1.0, v125
	v_rcp_f32_e32 v124, v124
	v_rcp_f32_e32 v125, v125
	s_nop 0
	v_cvt_pk_bf16_f32 v127, v124, v125
	v_mul_f32_e32 v122, 0xbfb8aa3b, v122
	v_mul_f32_e32 v123, 0xbfb8aa3b, v123
	v_exp_f32_e32 v122, v122
	v_exp_f32_e32 v123, v123
	v_add_f32_e32 v122, 1.0, v122
	v_add_f32_e32 v123, 1.0, v123
	v_rcp_f32_e32 v122, v122
	v_rcp_f32_e32 v123, v123
	s_nop 0
	v_cvt_pk_bf16_f32 v126, v122, v123
	global_store_dwordx4 v[156:157], v[126:129], off nt
	v_mul_f32_e32 v120, 0xbfb8aa3b, v120
	v_mul_f32_e32 v121, 0xbfb8aa3b, v121
	v_exp_f32_e32 v120, v120
	v_exp_f32_e32 v121, v121
	v_add_f32_e32 v120, 1.0, v120
	v_add_f32_e32 v121, 1.0, v121
	v_rcp_f32_e32 v120, v120
	v_rcp_f32_e32 v121, v121
	s_nop 0
	v_cvt_pk_bf16_f32 v121, v120, v121
	v_mul_f32_e32 v118, 0xbfb8aa3b, v118
	v_mul_f32_e32 v119, 0xbfb8aa3b, v119
	v_exp_f32_e32 v118, v118
	v_exp_f32_e32 v119, v119
	v_add_f32_e32 v118, 1.0, v118
	v_add_f32_e32 v119, 1.0, v119
	v_rcp_f32_e32 v118, v118
	v_rcp_f32_e32 v119, v119
	s_nop 0
	v_cvt_pk_bf16_f32 v120, v118, v119
	v_mul_f32_e32 v116, 0xbfb8aa3b, v116
	v_mul_f32_e32 v117, 0xbfb8aa3b, v117
	v_exp_f32_e32 v116, v116
	v_exp_f32_e32 v117, v117
	v_add_f32_e32 v116, 1.0, v116
	v_add_f32_e32 v117, 1.0, v117
	v_rcp_f32_e32 v116, v116
	v_rcp_f32_e32 v117, v117
	s_nop 0
	v_cvt_pk_bf16_f32 v119, v116, v117
	v_mul_f32_e32 v114, 0xbfb8aa3b, v114
	v_mul_f32_e32 v115, 0xbfb8aa3b, v115
	v_exp_f32_e32 v114, v114
	v_exp_f32_e32 v115, v115
	v_add_f32_e32 v114, 1.0, v114
	v_add_f32_e32 v115, 1.0, v115
	v_rcp_f32_e32 v114, v114
	v_rcp_f32_e32 v115, v115
	s_nop 0
	v_cvt_pk_bf16_f32 v118, v114, v115
	global_store_dwordx4 v[156:157], v[118:121], off offset:1024 nt
	v_mul_f32_e32 v112, 0xbfb8aa3b, v112
	v_mul_f32_e32 v113, 0xbfb8aa3b, v113
	v_exp_f32_e32 v112, v112
	v_exp_f32_e32 v113, v113
	v_add_f32_e32 v112, 1.0, v112
	v_add_f32_e32 v113, 1.0, v113
	v_rcp_f32_e32 v112, v112
	v_rcp_f32_e32 v113, v113
	s_nop 0
	v_cvt_pk_bf16_f32 v113, v112, v113
	v_mul_f32_e32 v110, 0xbfb8aa3b, v110
	v_mul_f32_e32 v111, 0xbfb8aa3b, v111
	v_exp_f32_e32 v110, v110
	v_exp_f32_e32 v111, v111
	v_add_f32_e32 v110, 1.0, v110
	v_add_f32_e32 v111, 1.0, v111
	v_rcp_f32_e32 v110, v110
	v_rcp_f32_e32 v111, v111
	s_nop 0
	v_cvt_pk_bf16_f32 v112, v110, v111
	v_mul_f32_e32 v108, 0xbfb8aa3b, v108
	v_mul_f32_e32 v109, 0xbfb8aa3b, v109
	v_exp_f32_e32 v108, v108
	v_exp_f32_e32 v109, v109
	v_add_f32_e32 v108, 1.0, v108
	v_add_f32_e32 v109, 1.0, v109
	v_rcp_f32_e32 v108, v108
	v_rcp_f32_e32 v109, v109
	s_nop 0
	v_cvt_pk_bf16_f32 v111, v108, v109
	v_mul_f32_e32 v106, 0xbfb8aa3b, v106
	v_mul_f32_e32 v107, 0xbfb8aa3b, v107
	v_exp_f32_e32 v106, v106
	v_exp_f32_e32 v107, v107
	v_add_f32_e32 v106, 1.0, v106
	v_add_f32_e32 v107, 1.0, v107
	v_rcp_f32_e32 v106, v106
	v_rcp_f32_e32 v107, v107
	s_nop 0
	v_cvt_pk_bf16_f32 v110, v106, v107
	global_store_dwordx4 v[156:157], v[110:113], off offset:2048 nt
	v_mul_f32_e32 v104, 0xbfb8aa3b, v104
	v_mul_f32_e32 v105, 0xbfb8aa3b, v105
	v_exp_f32_e32 v104, v104
	v_exp_f32_e32 v105, v105
	v_add_f32_e32 v104, 1.0, v104
	v_add_f32_e32 v105, 1.0, v105
	v_rcp_f32_e32 v104, v104
	v_rcp_f32_e32 v105, v105
	s_nop 0
	v_cvt_pk_bf16_f32 v105, v104, v105
	v_mul_f32_e32 v102, 0xbfb8aa3b, v102
	v_mul_f32_e32 v103, 0xbfb8aa3b, v103
	v_exp_f32_e32 v102, v102
	v_exp_f32_e32 v103, v103
	v_add_f32_e32 v102, 1.0, v102
	v_add_f32_e32 v103, 1.0, v103
	v_rcp_f32_e32 v102, v102
	v_rcp_f32_e32 v103, v103
	s_nop 0
	v_cvt_pk_bf16_f32 v104, v102, v103
	v_mul_f32_e32 v100, 0xbfb8aa3b, v100
	v_mul_f32_e32 v101, 0xbfb8aa3b, v101
	v_exp_f32_e32 v100, v100
	v_exp_f32_e32 v101, v101
	v_add_f32_e32 v100, 1.0, v100
	v_add_f32_e32 v101, 1.0, v101
	v_rcp_f32_e32 v100, v100
	v_rcp_f32_e32 v101, v101
	s_nop 0
	v_cvt_pk_bf16_f32 v103, v100, v101
	v_mul_f32_e32 v98, 0xbfb8aa3b, v98
	v_mul_f32_e32 v99, 0xbfb8aa3b, v99
	v_exp_f32_e32 v98, v98
	v_exp_f32_e32 v99, v99
	v_add_f32_e32 v98, 1.0, v98
	v_add_f32_e32 v99, 1.0, v99
	v_rcp_f32_e32 v98, v98
	v_rcp_f32_e32 v99, v99
	s_nop 0
	v_cvt_pk_bf16_f32 v102, v98, v99
	global_store_dwordx4 v[156:157], v[102:105], off offset:3072 nt
	global_store_dwordx4 v[92:93], v[94:97], off offset:-4096 nt
	v_mul_f32_e32 v88, 0xbfb8aa3b, v88
	v_mul_f32_e32 v89, 0xbfb8aa3b, v89
	v_exp_f32_e32 v88, v88
	v_exp_f32_e32 v89, v89
	v_add_f32_e32 v88, 1.0, v88
	v_add_f32_e32 v89, 1.0, v89
	v_rcp_f32_e32 v88, v88
	v_rcp_f32_e32 v89, v89
	s_nop 0
	v_cvt_pk_bf16_f32 v89, v88, v89
	v_mul_f32_e32 v86, 0xbfb8aa3b, v86
	v_mul_f32_e32 v87, 0xbfb8aa3b, v87
	v_exp_f32_e32 v86, v86
	v_exp_f32_e32 v87, v87
	v_add_f32_e32 v86, 1.0, v86
	v_add_f32_e32 v87, 1.0, v87
	v_rcp_f32_e32 v86, v86
	v_rcp_f32_e32 v87, v87
	s_nop 0
	v_cvt_pk_bf16_f32 v88, v86, v87
	v_mul_f32_e32 v84, 0xbfb8aa3b, v84
	v_mul_f32_e32 v85, 0xbfb8aa3b, v85
	v_exp_f32_e32 v84, v84
	v_exp_f32_e32 v85, v85
	v_add_f32_e32 v84, 1.0, v84
	v_add_f32_e32 v85, 1.0, v85
	v_rcp_f32_e32 v84, v84
	v_rcp_f32_e32 v85, v85
	s_nop 0
	v_cvt_pk_bf16_f32 v87, v84, v85
	v_mul_f32_e32 v82, 0xbfb8aa3b, v82
	v_mul_f32_e32 v83, 0xbfb8aa3b, v83
	v_exp_f32_e32 v82, v82
	v_exp_f32_e32 v83, v83
	v_add_f32_e32 v82, 1.0, v82
	v_add_f32_e32 v83, 1.0, v83
	v_rcp_f32_e32 v82, v82
	v_rcp_f32_e32 v83, v83
	s_nop 0
	v_cvt_pk_bf16_f32 v86, v82, v83
	global_store_dwordx4 v[90:91], v[86:89], off offset:1024 nt
	v_mul_f32_e32 v80, 0xbfb8aa3b, v80
	v_mul_f32_e32 v81, 0xbfb8aa3b, v81
	v_exp_f32_e32 v80, v80
	v_exp_f32_e32 v81, v81
	v_add_f32_e32 v80, 1.0, v80
	v_add_f32_e32 v81, 1.0, v81
	v_rcp_f32_e32 v80, v80
	v_rcp_f32_e32 v81, v81
	s_nop 0
	v_cvt_pk_bf16_f32 v81, v80, v81
	v_mul_f32_e32 v78, 0xbfb8aa3b, v78
	v_mul_f32_e32 v79, 0xbfb8aa3b, v79
	v_exp_f32_e32 v78, v78
	v_exp_f32_e32 v79, v79
	v_add_f32_e32 v78, 1.0, v78
	v_add_f32_e32 v79, 1.0, v79
	v_rcp_f32_e32 v78, v78
	v_rcp_f32_e32 v79, v79
	s_nop 0
	v_cvt_pk_bf16_f32 v80, v78, v79
	v_mul_f32_e32 v76, 0xbfb8aa3b, v76
	v_mul_f32_e32 v77, 0xbfb8aa3b, v77
	v_exp_f32_e32 v76, v76
	v_exp_f32_e32 v77, v77
	v_add_f32_e32 v76, 1.0, v76
	v_add_f32_e32 v77, 1.0, v77
	v_rcp_f32_e32 v76, v76
	v_rcp_f32_e32 v77, v77
	s_nop 0
	v_cvt_pk_bf16_f32 v79, v76, v77
	v_mul_f32_e32 v74, 0xbfb8aa3b, v74
	v_mul_f32_e32 v75, 0xbfb8aa3b, v75
	v_exp_f32_e32 v74, v74
	v_exp_f32_e32 v75, v75
	v_add_f32_e32 v74, 1.0, v74
	v_add_f32_e32 v75, 1.0, v75
	v_rcp_f32_e32 v74, v74
	v_rcp_f32_e32 v75, v75
	s_nop 0
	v_cvt_pk_bf16_f32 v78, v74, v75
	global_store_dwordx4 v[90:91], v[78:81], off offset:2048 nt
	v_mul_f32_e32 v72, 0xbfb8aa3b, v72
	v_mul_f32_e32 v73, 0xbfb8aa3b, v73
	v_exp_f32_e32 v72, v72
	v_exp_f32_e32 v73, v73
	v_add_f32_e32 v72, 1.0, v72
	v_add_f32_e32 v73, 1.0, v73
	v_rcp_f32_e32 v72, v72
	v_rcp_f32_e32 v73, v73
	s_nop 0
	v_cvt_pk_bf16_f32 v73, v72, v73
	v_mul_f32_e32 v70, 0xbfb8aa3b, v70
	v_mul_f32_e32 v71, 0xbfb8aa3b, v71
	v_exp_f32_e32 v70, v70
	v_exp_f32_e32 v71, v71
	v_add_f32_e32 v70, 1.0, v70
	v_add_f32_e32 v71, 1.0, v71
	v_rcp_f32_e32 v70, v70
	v_rcp_f32_e32 v71, v71
	s_nop 0
	v_cvt_pk_bf16_f32 v72, v70, v71
	v_mul_f32_e32 v68, 0xbfb8aa3b, v68
	v_mul_f32_e32 v69, 0xbfb8aa3b, v69
	v_exp_f32_e32 v68, v68
	v_exp_f32_e32 v69, v69
	v_add_f32_e32 v68, 1.0, v68
	v_add_f32_e32 v69, 1.0, v69
	v_rcp_f32_e32 v68, v68
	v_rcp_f32_e32 v69, v69
	s_nop 0
	v_cvt_pk_bf16_f32 v71, v68, v69
	v_mul_f32_e32 v66, 0xbfb8aa3b, v66
	v_mul_f32_e32 v67, 0xbfb8aa3b, v67
	v_exp_f32_e32 v66, v66
	v_exp_f32_e32 v67, v67
	v_add_f32_e32 v66, 1.0, v66
	v_add_f32_e32 v67, 1.0, v67
	v_rcp_f32_e32 v66, v66
	v_rcp_f32_e32 v67, v67
	s_nop 0
	v_cvt_pk_bf16_f32 v70, v66, v67
	global_store_dwordx4 v[90:91], v[70:73], off offset:3072 nt
	v_mul_f32_e32 v64, 0xbfb8aa3b, v64
	v_mul_f32_e32 v65, 0xbfb8aa3b, v65
	v_exp_f32_e32 v64, v64
	v_exp_f32_e32 v65, v65
	v_add_f32_e32 v64, 1.0, v64
	v_add_f32_e32 v65, 1.0, v65
	v_rcp_f32_e32 v64, v64
	v_rcp_f32_e32 v65, v65
	s_nop 0
	v_cvt_pk_bf16_f32 v65, v64, v65
	v_mul_f32_e32 v62, 0xbfb8aa3b, v62
	v_mul_f32_e32 v63, 0xbfb8aa3b, v63
	v_exp_f32_e32 v62, v62
	v_exp_f32_e32 v63, v63
	v_add_f32_e32 v62, 1.0, v62
	v_add_f32_e32 v63, 1.0, v63
	v_rcp_f32_e32 v62, v62
	v_rcp_f32_e32 v63, v63
	s_nop 0
	v_cvt_pk_bf16_f32 v64, v62, v63
	v_mul_f32_e32 v60, 0xbfb8aa3b, v60
	v_mul_f32_e32 v61, 0xbfb8aa3b, v61
	v_exp_f32_e32 v60, v60
	v_exp_f32_e32 v61, v61
	v_add_f32_e32 v60, 1.0, v60
	v_add_f32_e32 v61, 1.0, v61
	v_rcp_f32_e32 v60, v60
	v_rcp_f32_e32 v61, v61
	s_nop 0
	v_cvt_pk_bf16_f32 v63, v60, v61
	v_mul_f32_e32 v58, 0xbfb8aa3b, v58
	v_mul_f32_e32 v59, 0xbfb8aa3b, v59
	v_exp_f32_e32 v58, v58
	v_exp_f32_e32 v59, v59
	v_add_f32_e32 v58, 1.0, v58
	v_add_f32_e32 v59, 1.0, v59
	v_rcp_f32_e32 v58, v58
	v_rcp_f32_e32 v59, v59
	s_nop 0
	v_cvt_pk_bf16_f32 v62, v58, v59
	global_store_dwordx4 v[92:93], v[62:65], off nt
	v_mul_f32_e32 v56, 0xbfb8aa3b, v56
	v_mul_f32_e32 v57, 0xbfb8aa3b, v57
	v_exp_f32_e32 v56, v56
	v_exp_f32_e32 v57, v57
	v_add_f32_e32 v56, 1.0, v56
	v_add_f32_e32 v57, 1.0, v57
	v_rcp_f32_e32 v56, v56
	v_rcp_f32_e32 v57, v57
	s_nop 0
	v_cvt_pk_bf16_f32 v57, v56, v57
	v_mul_f32_e32 v54, 0xbfb8aa3b, v54
	v_mul_f32_e32 v55, 0xbfb8aa3b, v55
	v_exp_f32_e32 v54, v54
	v_exp_f32_e32 v55, v55
	v_add_f32_e32 v54, 1.0, v54
	v_add_f32_e32 v55, 1.0, v55
	v_rcp_f32_e32 v54, v54
	v_rcp_f32_e32 v55, v55
	s_nop 0
	v_cvt_pk_bf16_f32 v56, v54, v55
	v_mul_f32_e32 v52, 0xbfb8aa3b, v52
	v_mul_f32_e32 v53, 0xbfb8aa3b, v53
	v_exp_f32_e32 v52, v52
	v_exp_f32_e32 v53, v53
	v_add_f32_e32 v52, 1.0, v52
	v_add_f32_e32 v53, 1.0, v53
	v_rcp_f32_e32 v52, v52
	v_rcp_f32_e32 v53, v53
	s_nop 0
	v_cvt_pk_bf16_f32 v55, v52, v53
	v_mul_f32_e32 v50, 0xbfb8aa3b, v50
	v_mul_f32_e32 v51, 0xbfb8aa3b, v51
	v_exp_f32_e32 v50, v50
	v_exp_f32_e32 v51, v51
	v_add_f32_e32 v50, 1.0, v50
	v_add_f32_e32 v51, 1.0, v51
	v_rcp_f32_e32 v50, v50
	v_rcp_f32_e32 v51, v51
	s_nop 0
	v_cvt_pk_bf16_f32 v54, v50, v51
	global_store_dwordx4 v[92:93], v[54:57], off offset:1024 nt
	v_mul_f32_e32 v48, 0xbfb8aa3b, v48
	v_mul_f32_e32 v49, 0xbfb8aa3b, v49
	v_exp_f32_e32 v48, v48
	v_exp_f32_e32 v49, v49
	v_add_f32_e32 v48, 1.0, v48
	v_add_f32_e32 v49, 1.0, v49
	v_rcp_f32_e32 v48, v48
	v_rcp_f32_e32 v49, v49
	s_nop 0
	v_cvt_pk_bf16_f32 v49, v48, v49
	v_mul_f32_e32 v46, 0xbfb8aa3b, v46
	v_mul_f32_e32 v47, 0xbfb8aa3b, v47
	v_exp_f32_e32 v46, v46
	v_exp_f32_e32 v47, v47
	v_add_f32_e32 v46, 1.0, v46
	v_add_f32_e32 v47, 1.0, v47
	v_rcp_f32_e32 v46, v46
	v_rcp_f32_e32 v47, v47
	s_nop 0
	v_cvt_pk_bf16_f32 v48, v46, v47
	v_mul_f32_e32 v44, 0xbfb8aa3b, v44
	v_mul_f32_e32 v45, 0xbfb8aa3b, v45
	v_exp_f32_e32 v44, v44
	v_exp_f32_e32 v45, v45
	v_add_f32_e32 v44, 1.0, v44
	v_add_f32_e32 v45, 1.0, v45
	v_rcp_f32_e32 v44, v44
	v_rcp_f32_e32 v45, v45
	s_nop 0
	v_cvt_pk_bf16_f32 v47, v44, v45
	v_mul_f32_e32 v42, 0xbfb8aa3b, v42
	v_mul_f32_e32 v43, 0xbfb8aa3b, v43
	v_exp_f32_e32 v42, v42
	v_exp_f32_e32 v43, v43
	v_add_f32_e32 v42, 1.0, v42
	v_add_f32_e32 v43, 1.0, v43
	v_rcp_f32_e32 v42, v42
	v_rcp_f32_e32 v43, v43
	s_nop 0
	v_cvt_pk_bf16_f32 v46, v42, v43
	global_store_dwordx4 v[92:93], v[46:49], off offset:2048 nt
	v_mul_f32_e32 v40, 0xbfb8aa3b, v40
	v_mul_f32_e32 v41, 0xbfb8aa3b, v41
	v_exp_f32_e32 v40, v40
	v_exp_f32_e32 v41, v41
	v_add_f32_e32 v40, 1.0, v40
	v_add_f32_e32 v41, 1.0, v41
	v_rcp_f32_e32 v40, v40
	v_rcp_f32_e32 v41, v41
	s_nop 0
	v_cvt_pk_bf16_f32 v41, v40, v41
	v_mul_f32_e32 v38, 0xbfb8aa3b, v38
	v_mul_f32_e32 v39, 0xbfb8aa3b, v39
	v_exp_f32_e32 v38, v38
	v_exp_f32_e32 v39, v39
	v_add_f32_e32 v38, 1.0, v38
	v_add_f32_e32 v39, 1.0, v39
	v_rcp_f32_e32 v38, v38
	v_rcp_f32_e32 v39, v39
	s_nop 0
	v_cvt_pk_bf16_f32 v40, v38, v39
	v_mul_f32_e32 v36, 0xbfb8aa3b, v36
	v_mul_f32_e32 v37, 0xbfb8aa3b, v37
	v_exp_f32_e32 v36, v36
	v_exp_f32_e32 v37, v37
	v_add_f32_e32 v36, 1.0, v36
	v_add_f32_e32 v37, 1.0, v37
	v_rcp_f32_e32 v36, v36
	v_rcp_f32_e32 v37, v37
	s_nop 0
	v_cvt_pk_bf16_f32 v39, v36, v37
	v_mul_f32_e32 v34, 0xbfb8aa3b, v34
	v_mul_f32_e32 v35, 0xbfb8aa3b, v35
	v_exp_f32_e32 v34, v34
	v_exp_f32_e32 v35, v35
	v_add_f32_e32 v34, 1.0, v34
	v_add_f32_e32 v35, 1.0, v35
	v_rcp_f32_e32 v34, v34
	v_rcp_f32_e32 v35, v35
	s_nop 0
	v_cvt_pk_bf16_f32 v38, v34, v35
	global_store_dwordx4 v[92:93], v[38:41], off offset:3072 nt
	v_mul_f32_e32 v28, 0xbfb8aa3b, v28
	v_mul_f32_e32 v29, 0xbfb8aa3b, v29
	v_exp_f32_e32 v28, v28
	v_exp_f32_e32 v29, v29
	v_add_f32_e32 v28, 1.0, v28
	v_add_f32_e32 v29, 1.0, v29
	v_rcp_f32_e32 v28, v28
	v_rcp_f32_e32 v29, v29
	s_nop 0
	v_cvt_pk_bf16_f32 v31, v28, v29
	v_addc_co_u32_e32 v27, vcc, 0, v157, vcc
	global_store_dwordx4 v[26:27], v[30:33], off nt
	v_mul_f32_e32 v24, 0xbfb8aa3b, v24
	v_mul_f32_e32 v25, 0xbfb8aa3b, v25
	v_exp_f32_e32 v24, v24
	v_exp_f32_e32 v25, v25
	v_add_f32_e32 v24, 1.0, v24
	v_add_f32_e32 v25, 1.0, v25
	v_rcp_f32_e32 v24, v24
	v_rcp_f32_e32 v25, v25
	s_nop 0
	v_cvt_pk_bf16_f32 v25, v24, v25
	v_mul_f32_e32 v22, 0xbfb8aa3b, v22
	v_mul_f32_e32 v23, 0xbfb8aa3b, v23
	v_exp_f32_e32 v22, v22
	v_exp_f32_e32 v23, v23
	v_add_f32_e32 v22, 1.0, v22
	v_add_f32_e32 v23, 1.0, v23
	v_rcp_f32_e32 v22, v22
	v_rcp_f32_e32 v23, v23
	s_nop 0
	v_cvt_pk_bf16_f32 v24, v22, v23
	v_mul_f32_e32 v20, 0xbfb8aa3b, v20
	v_mul_f32_e32 v21, 0xbfb8aa3b, v21
	v_exp_f32_e32 v20, v20
	v_exp_f32_e32 v21, v21
	v_add_f32_e32 v20, 1.0, v20
	v_add_f32_e32 v21, 1.0, v21
	v_rcp_f32_e32 v20, v20
	v_rcp_f32_e32 v21, v21
	s_nop 0
	v_cvt_pk_bf16_f32 v23, v20, v21
	v_mul_f32_e32 v18, 0xbfb8aa3b, v18
	v_mul_f32_e32 v19, 0xbfb8aa3b, v19
	v_exp_f32_e32 v18, v18
	v_exp_f32_e32 v19, v19
	v_add_f32_e32 v18, 1.0, v18
	v_add_f32_e32 v19, 1.0, v19
	v_rcp_f32_e32 v18, v18
	v_rcp_f32_e32 v19, v19
	s_nop 0
	v_cvt_pk_bf16_f32 v22, v18, v19
	global_store_dwordx4 v[26:27], v[22:25], off offset:1024 nt
	v_mul_f32_e32 v16, 0xbfb8aa3b, v16
	v_mul_f32_e32 v17, 0xbfb8aa3b, v17
	v_exp_f32_e32 v16, v16
	v_exp_f32_e32 v17, v17
	v_add_f32_e32 v16, 1.0, v16
	v_add_f32_e32 v17, 1.0, v17
	v_rcp_f32_e32 v16, v16
	v_rcp_f32_e32 v17, v17
	s_nop 0
	v_cvt_pk_bf16_f32 v17, v16, v17
	v_mul_f32_e32 v14, 0xbfb8aa3b, v14
	v_mul_f32_e32 v15, 0xbfb8aa3b, v15
	v_exp_f32_e32 v14, v14
	v_exp_f32_e32 v15, v15
	v_add_f32_e32 v14, 1.0, v14
	v_add_f32_e32 v15, 1.0, v15
	v_rcp_f32_e32 v14, v14
	v_rcp_f32_e32 v15, v15
	s_nop 0
	v_cvt_pk_bf16_f32 v16, v14, v15
	v_mul_f32_e32 v12, 0xbfb8aa3b, v12
	v_mul_f32_e32 v13, 0xbfb8aa3b, v13
	v_exp_f32_e32 v12, v12
	v_exp_f32_e32 v13, v13
	v_add_f32_e32 v12, 1.0, v12
	v_add_f32_e32 v13, 1.0, v13
	v_rcp_f32_e32 v12, v12
	v_rcp_f32_e32 v13, v13
	s_nop 0
	v_cvt_pk_bf16_f32 v15, v12, v13
	v_mul_f32_e32 v10, 0xbfb8aa3b, v10
	v_mul_f32_e32 v11, 0xbfb8aa3b, v11
	v_exp_f32_e32 v10, v10
	v_exp_f32_e32 v11, v11
	v_add_f32_e32 v10, 1.0, v10
	v_add_f32_e32 v11, 1.0, v11
	v_rcp_f32_e32 v10, v10
	v_rcp_f32_e32 v11, v11
	s_nop 0
	v_cvt_pk_bf16_f32 v14, v10, v11
	global_store_dwordx4 v[26:27], v[14:17], off offset:2048 nt
	v_mul_f32_e32 v4, 0xbfb8aa3b, v4
	v_mul_f32_e32 v5, 0xbfb8aa3b, v5
	v_exp_f32_e32 v4, v4
	v_exp_f32_e32 v5, v5
	v_add_f32_e32 v4, 1.0, v4
	v_add_f32_e32 v5, 1.0, v5
	v_rcp_f32_e32 v4, v4
	v_rcp_f32_e32 v5, v5
	s_nop 0
	v_cvt_pk_bf16_f32 v5, v4, v5
	v_mul_f32_e32 v2, 0xbfb8aa3b, v2
	v_mul_f32_e32 v3, 0xbfb8aa3b, v3
	v_exp_f32_e32 v2, v2
	v_exp_f32_e32 v3, v3
	v_add_f32_e32 v2, 1.0, v2
	v_add_f32_e32 v3, 1.0, v3
	v_rcp_f32_e32 v2, v2
	v_rcp_f32_e32 v3, v3
	s_nop 0
	v_cvt_pk_bf16_f32 v4, v2, v3
	v_mul_f32_e32 v8, 0xbfb8aa3b, v8
	v_mul_f32_e32 v9, 0xbfb8aa3b, v9
	v_exp_f32_e32 v8, v8
	v_exp_f32_e32 v9, v9
	v_add_f32_e32 v8, 1.0, v8
	v_add_f32_e32 v9, 1.0, v9
	v_rcp_f32_e32 v8, v8
	v_rcp_f32_e32 v9, v9
	s_nop 0
	v_cvt_pk_bf16_f32 v3, v8, v9
	v_mul_f32_e32 v6, 0xbfb8aa3b, v6
	v_mul_f32_e32 v7, 0xbfb8aa3b, v7
	v_exp_f32_e32 v6, v6
	v_exp_f32_e32 v7, v7
	v_add_f32_e32 v6, 1.0, v6
	v_add_f32_e32 v7, 1.0, v7
	v_rcp_f32_e32 v6, v6
	v_rcp_f32_e32 v7, v7
	s_nop 0
	v_cvt_pk_bf16_f32 v2, v6, v7
	global_store_dwordx4 v[26:27], v[2:5], off offset:3072 nt
	s_mov_b32 s100, 1
	s_branch .LBB0_234
